# scan loader waves raised to the same priority as the compute waves inside the chunk loop
# baseline (speedup 1.0000x reference)
.LBB0_1102:
	v_ashrrev_i32_e32 v45, 31, v44
	v_lshlrev_b64 v[26:27], 1, v[44:45]
	v_or_b32_e32 v26, s37, v26
	v_readlane_b32 s2, v252, 0
	v_readlane_b32 s4, v252, 6
	v_or_b32_e32 v43, s61, v90
	v_sub_u32_e32 v46, s27, v90
	v_lshlrev_b64 v[30:31], 10, v[26:27]
	v_readlane_b32 s3, v252, 1
	v_lshlrev_b64 v[26:27], 9, v[26:27]
	v_readlane_b32 s5, v252, 7
	v_cndmask_b32_e64 v46, v46, v43, s[16:17]
	v_lshl_add_u64 v[28:29], s[2:3], 0, v[30:31]
	v_lshl_add_u64 v[26:27], s[4:5], 0, v[26:27]
	v_mov_b32_e32 v41, v1
	v_ashrrev_i32_e32 v47, 31, v46
	v_readlane_b32 s8, v252, 10
	v_lshl_add_u64 v[28:29], v[28:29], 0, v[0:1]
	v_lshl_add_u64 v[32:33], v[26:27], 0, v[40:41]
	v_readlane_b32 s10, v252, 20
	v_readlane_b32 s12, v252, 22
	v_readlane_b32 s6, v252, 8
	v_lshlrev_b64 v[46:47], 9, v[46:47]
	v_readlane_b32 s9, v252, 11
	v_add_u32_e32 v124, 0x1b800, v123
	s_nop 0
	v_readfirstlane_b32 s98, v124
	s_mov_b32 m0, s98
	s_nop 0
	global_load_lds_dwordx4 v[28:29], off
	s_nop 0
	global_load_dwordx2 v[82:83], v[32:33], off
	v_lshlrev_b64 v[32:33], 10, v[44:45]
	v_readlane_b32 s11, v252, 21
	v_readlane_b32 s13, v252, 23
	v_lshlrev_b64 v[44:45], 9, v[44:45]
	v_readlane_b32 s7, v252, 9
	v_lshl_add_u64 v[46:47], s[8:9], 0, v[46:47]
	s_mov_b32 s27, s21
	v_lshl_add_u64 v[32:33], s[10:11], 0, v[32:33]
	v_lshl_add_u64 v[30:31], s[12:13], 0, v[30:31]
	v_lshl_add_u64 v[44:45], s[6:7], 0, v[44:45]
	v_lshl_add_u64 v[46:47], v[46:47], 0, s[26:27]
	s_mov_b32 s49, s21
	v_lshl_add_u64 v[32:33], v[32:33], 0, v[0:1]
	v_lshl_add_u64 v[34:35], v[30:31], 0, v[0:1]
	v_lshl_add_u64 v[44:45], v[44:45], 0, v[40:41]
	v_lshl_add_u64 v[46:47], v[46:47], 0, s[48:49]
	v_mov_b32_e32 v43, v1
	v_add_u32_e32 v124, 0x1c800, v123
	s_nop 0
	v_readfirstlane_b32 s98, v124
	s_mov_b32 m0, s98
	s_nop 0
	global_load_lds_dwordx4 v[32:33], off
	s_nop 0
	v_add_u32_e32 v124, 0x1d800, v123
	s_nop 0
	v_readfirstlane_b32 s98, v124
	s_mov_b32 m0, s98
	s_nop 0
	global_load_lds_dwordx4 v[34:35], off
	v_lshl_add_u64 v[46:47], v[46:47], 0, v[42:43]
	global_load_dwordx2 v[84:85], v[44:45], off
	global_load_dwordx2 v[86:87], v[46:47], off
	s_lshl_b32 s20, s37, 10
	v_lshl_add_u64 v[60:61], s[2:3], 0, v[0:1]
	s_add_u32 s2, s8, s26
	s_addc_u32 s3, s9, 0
	s_add_u32 s26, s2, s48
	s_addc_u32 s27, s3, 0
	v_readlane_b32 s2, v252, 14
	v_readlane_b32 s3, v252, 15
	s_add_u32 s2, s2, s20
	s_addc_u32 s3, s3, 0
	s_lshl_b32 s48, s60, 2
	s_add_u32 s2, s2, s48
	s_addc_u32 s3, s3, 0
	s_lshl_b32 s50, s33, 2
	s_waitcnt vmcnt(12)
	s_waitcnt lgkmcnt(0)
	s_barrier
	v_lshl_add_u64 v[70:71], s[26:27], 0, v[42:43]
	s_add_u32 s26, s2, s50
	v_lshl_add_u64 v[64:65], s[10:11], 0, v[0:1]
	v_lshl_add_u64 v[66:67], s[12:13], 0, v[0:1]
	v_lshlrev_b32_e32 v0, 6, v39
	v_lshrrev_b32_e32 v94, 2, v39
	s_addc_u32 s27, s3, 0
	v_mov_b32_e32 v39, v1
	v_lshl_add_u64 v[62:63], s[4:5], 0, v[40:41]
	v_lshl_add_u64 v[68:69], s[6:7], 0, v[40:41]
	v_and_b32_e32 v93, 0xc0, v0
	v_add_u32_e32 v0, 0, v0
	v_lshl_add_u64 v[72:73], s[26:27], 0, v[38:39]
	s_sub_i32 s98, 1, s37
	s_sub_i32 s98, s98, s37
	s_ashr_i32 s99, s98, 31
	v_mov_b32_e32 v112, s98
	v_mov_b32_e32 v113, s99
	s_cmp_eq_u32 s37, 0
	s_cselect_b32 s98, 64, 0xbf
	s_add_i32 s98, s98, s25
	v_mov_b32_e32 v110, s98
	v_mad_i32_i24 v111, v55, v112, v110
	v_and_b32_e32 v108, 63, v232
	v_lshrrev_b32_e32 v108, 2, v108
	v_mad_i32_i24 v109, v108, v112, v110
	v_lshl_or_b32 v108, v111, 1, s37
	s_movk_i32 s98, 0x400
	s_movk_i32 s99, 0x200
	v_mad_u64_u32 v[96:97], vcc, v108, s98, v[60:61]
	v_mad_u64_u32 v[98:99], vcc, v108, s99, v[62:63]
	v_mad_u64_u32 v[100:101], vcc, v111, s98, v[64:65]
	v_mad_u64_u32 v[102:103], vcc, v108, s98, v[66:67]
	v_mad_u64_u32 v[104:105], vcc, v111, s99, v[68:69]
	v_mad_u64_u32 v[106:107], vcc, v109, s99, v[70:71]
	s_cmp_eq_u32 s37, 0
	s_cselect_b32 s98, 0, 0xff
	s_add_i32 s98, s98, s25
	v_mov_b32_e32 v110, s98
	v_mad_i32_i24 v111, v55, v112, v110
	s_movk_i32 s98, 0x800
	v_mad_u64_u32 v[108:109], vcc, v111, s98, v[72:73]
	v_and_b32_e32 v126, 0xff, v232
	v_lshrrev_b32_e32 v127, 6, v126
	v_and_b32_e32 v128, 3, v126
	v_lshl_add_u32 v127, v127, 2, v128
	v_lshrrev_b32_e32 v128, 4, v126
	v_sub_u32_e32 v127, v127, v128
	v_mul_i32_i24_e32 v127, v127, v112
	v_lshlrev_b32_e32 v127, 11, v127
	v_bfe_u32 v128, v126, 2, 4
	v_and_b32_e32 v129, 15, v126
	v_sub_u32_e32 v128, v128, v129
	v_lshl_add_u32 v128, v128, 2, v127
	v_ashrrev_i32_e32 v129, 31, v128
	v_lshl_add_u64 v[108:109], v[128:129], 0, v[108:109]
	v_and_b32_e32 v125, 0xff, v232
	v_lshrrev_b32_e32 v130, 2, v125
	v_add_u32_e32 v126, 0, v130
	v_and_b32_e32 v126, 3, v126
	v_lshlrev_b32_e32 v126, 4, v126
	v_lshl_add_u32 v126, v125, 6, v126
	v_add_u32_e32 v127, 1, v130
	v_and_b32_e32 v127, 3, v127
	v_lshlrev_b32_e32 v127, 4, v127
	v_lshl_add_u32 v127, v125, 6, v127
	v_add_u32_e32 v128, 2, v130
	v_and_b32_e32 v128, 3, v128
	v_lshlrev_b32_e32 v128, 4, v128
	v_lshl_add_u32 v128, v125, 6, v128
	v_add_u32_e32 v129, 3, v130
	v_and_b32_e32 v129, 3, v129
	v_lshlrev_b32_e32 v129, 4, v129
	v_lshl_add_u32 v129, v125, 6, v129
	v_and_b32_e32 v125, 3, v232
	s_sub_i32 s98, s24, s25
	s_movk_i32 s99, 0x1000
	s_cmp_eq_u32 s37, 0
	s_cselect_b32 s99, 0xffffff00, s99
	s_add_i32 s98, s98, s99
	s_lshl_b32 s98, s98, 9
	s_ashr_i32 s99, s98, 31
	v_mov_b32_e32 v120, s98
	v_mov_b32_e32 v121, s99
	s_lshl_b32 s98, s98, 1
	v_mov_b32_e32 v118, s98
	v_mov_b32_e32 v119, s99
	s_lshl_b32 s98, s98, 1
	v_mov_b32_e32 v110, s98
	v_mov_b32_e32 v111, s99
	v_lshlrev_b32_e32 v112, 15, v112
	v_ashrrev_i32_e32 v114, 1, v112
	v_mov_b32_e32 v115, v113
	v_ashrrev_i32_e32 v116, 2, v112
	v_mov_b32_e32 v117, v113
	s_setprio 3
	s_mov_b32 s49, 0
	s_mov_b32 s51, 0
	s_branch .LBB0_1106

.LBB0_1277:
	s_setprio 0
	s_waitcnt vmcnt(6)
	ds_read_b128 v[2:5], v126 offset:59392
	s_waitcnt vmcnt(4)
	ds_read_b128 v[6:9], v127 offset:59392
	s_waitcnt vmcnt(3)
	ds_read_b128 v[10:13], v128 offset:59392
	ds_read_b128 v[14:17], v129 offset:59392
	s_or_b32 s2, s24, 15
	v_add_u32_e32 v0, s24, v55
	s_waitcnt lgkmcnt(2)
	v_pk_add_f32 v[4:5], v[4:5], v[8:9]
	v_pk_add_f32 v[2:3], v[2:3], v[6:7]
	s_waitcnt lgkmcnt(0)
	v_pk_add_f32 v[6:7], v[12:13], v[16:17]
	v_pk_add_f32 v[8:9], v[10:11], v[14:15]
	v_add_u32_e32 v0, 0xff0, v0
	v_sub_u32_e32 v18, s2, v55
	v_pk_add_f32 v[4:5], v[4:5], v[6:7]
	v_pk_add_f32 v[2:3], v[2:3], v[8:9]
	v_cndmask_b32_e64 v18, v18, v0, s[16:17]
	s_nop 1
	v_add_f32_dpp v2, v2, v2 quad_perm:[1,0,3,2] row_mask:0xf bank_mask:0xf bound_ctrl:1
	v_add_f32_dpp v3, v3, v3 quad_perm:[1,0,3,2] row_mask:0xf bank_mask:0xf bound_ctrl:1
	v_add_f32_dpp v4, v4, v4 quad_perm:[1,0,3,2] row_mask:0xf bank_mask:0xf bound_ctrl:1
	v_add_f32_dpp v5, v5, v5 quad_perm:[1,0,3,2] row_mask:0xf bank_mask:0xf bound_ctrl:1
	v_add_f32_dpp v2, v2, v2 quad_perm:[2,3,0,1] row_mask:0xf bank_mask:0xf bound_ctrl:1
	v_add_f32_dpp v3, v3, v3 quad_perm:[2,3,0,1] row_mask:0xf bank_mask:0xf bound_ctrl:1
	v_add_f32_dpp v4, v4, v4 quad_perm:[2,3,0,1] row_mask:0xf bank_mask:0xf bound_ctrl:1
	v_add_f32_dpp v5, v5, v5 quad_perm:[2,3,0,1] row_mask:0xf bank_mask:0xf bound_ctrl:1
	v_cmp_eq_u32_e64 s[2:3], 1, v125
	s_nop 1
	v_cndmask_b32_e64 v6, v2, v3, s[2:3]
	v_cmp_eq_u32_e64 s[2:3], 2, v125
	s_nop 1
	v_cndmask_b32_e64 v6, v6, v4, s[2:3]
	v_cmp_eq_u32_e64 s[2:3], 3, v125
	s_nop 1
	v_cndmask_b32_e64 v6, v6, v5, s[2:3]
	v_ashrrev_i32_e32 v19, 31, v18
	v_readlane_b32 s2, v252, 14
	v_lshlrev_b64 v[2:3], 11, v[18:19]
	v_readlane_b32 s3, v252, 15
	s_mov_b32 s49, s21
	s_mov_b32 s51, s21
	v_lshl_add_u64 v[2:3], s[2:3], 0, v[2:3]
	v_lshl_add_u64 v[2:3], v[2:3], 0, s[20:21]
	v_lshl_add_u64 v[2:3], v[2:3], 0, s[48:49]
	v_lshl_add_u64 v[2:3], v[2:3], 0, s[50:51]
	v_lshlrev_b32_e32 v0, 2, v54
	v_lshl_add_u64 v[2:3], v[2:3], 0, v[0:1]
	global_store_dword v[108:109], v6, off
	s_mov_b32 s20, 0x10000
